# row-norm loops: the four 16-byte chunks of each gain vector loaded together (one wait) instead of load+vmcnt(0) per chunk
# speedup vs baseline: 1.0282x; 1.0065x over previous
.LBB0_79:
	s_or_b64 exec, exec, s[24:25]
	s_waitcnt vmcnt(0)
	v_pk_mul_f32 v[46:47], v[20:21], v[20:21]
	v_pk_mul_f32 v[48:49], v[22:23], v[22:23]
	v_add_f32_e32 v3, v47, v46
	v_pk_mul_f32 v[50:51], v[24:25], v[24:25]
	v_add_f32_e32 v3, v48, v3
	v_add_f32_e32 v1, v51, v50
	v_add_f32_e32 v3, v49, v3
	global_load_dwordx4 v[48:51], v[38:39], off
	global_load_dwordx4 v[132:135], v[38:39], off offset:1024
	global_load_dwordx4 v[136:139], v[38:39], off offset:2048
	global_load_dwordx4 v[140:143], v[38:39], off offset:3072
	v_pk_mul_f32 v[52:53], v[26:27], v[26:27]
	v_pk_mul_f32 v[54:55], v[28:29], v[28:29]
	v_add_f32_e32 v1, v52, v1
	v_add_f32_e32 v1, v53, v1
	v_pk_mul_f32 v[56:57], v[30:31], v[30:31]
	v_add_f32_e32 v1, v3, v1
	v_add_f32_e32 v3, v55, v54
	v_add_f32_e32 v3, v56, v3
	v_pk_mul_f32 v[58:59], v[32:33], v[32:33]
	v_add_f32_e32 v3, v57, v3
	v_pk_mul_f32 v[60:61], v[34:35], v[34:35]
	v_add_f32_e32 v1, v1, v3
	v_add_f32_e32 v3, v59, v58
	v_add_f32_e32 v3, v60, v3
	v_add_f32_e32 v3, v61, v3
	v_add_f32_e32 v1, v1, v3
	v_and_b32_e32 v3, 64, v202
	v_add_u32_e32 v3, 64, v3
	v_xor_b32_e32 v46, 32, v202
	v_cmp_lt_i32_e32 vcc, v46, v3
	s_mov_b32 s4, 0x800000
	s_nop 0
	v_cndmask_b32_e32 v46, v202, v46, vcc
	v_lshlrev_b32_e32 v46, 2, v46
	ds_bpermute_b32 v46, v46, v1
	s_waitcnt lgkmcnt(0)
	v_add_f32_e32 v1, v1, v46
	v_xor_b32_e32 v46, 16, v202
	v_cmp_lt_i32_e32 vcc, v46, v3
	s_nop 1
	v_cndmask_b32_e32 v46, v202, v46, vcc
	v_lshlrev_b32_e32 v46, 2, v46
	ds_bpermute_b32 v46, v46, v1
	s_waitcnt lgkmcnt(0)
	v_add_f32_e32 v1, v1, v46
	v_xor_b32_e32 v46, 8, v202
	v_cmp_lt_i32_e32 vcc, v46, v3
	s_nop 1
	v_cndmask_b32_e32 v46, v202, v46, vcc
	v_lshlrev_b32_e32 v46, 2, v46
	ds_bpermute_b32 v46, v46, v1
	s_waitcnt lgkmcnt(0)
	v_add_f32_e32 v1, v1, v46
	v_xor_b32_e32 v46, 4, v202
	v_cmp_lt_i32_e32 vcc, v46, v3
	s_nop 1
	v_cndmask_b32_e32 v46, v202, v46, vcc
	v_lshlrev_b32_e32 v46, 2, v46
	ds_bpermute_b32 v46, v46, v1
	s_waitcnt lgkmcnt(0)
	v_add_f32_e32 v1, v1, v46
	v_xor_b32_e32 v46, 2, v202
	v_cmp_lt_i32_e32 vcc, v46, v3
	s_nop 1
	v_cndmask_b32_e32 v46, v202, v46, vcc
	v_lshlrev_b32_e32 v46, 2, v46
	ds_bpermute_b32 v46, v46, v1
	s_waitcnt lgkmcnt(0)
	v_add_f32_e32 v1, v1, v46
	v_xor_b32_e32 v46, 1, v202
	v_cmp_lt_i32_e32 vcc, v46, v3
	s_nop 1
	v_cndmask_b32_e32 v3, v202, v46, vcc
	v_lshlrev_b32_e32 v3, 2, v3
	ds_bpermute_b32 v3, v3, v1
	s_waitcnt lgkmcnt(0)
	v_add_f32_e32 v1, v1, v3
	v_fmamk_f32 v1, v1, 0x3a800000, v198
	v_cmp_gt_f32_e32 vcc, s4, v1
	v_mul_f32_e32 v3, 0x4b800000, v1
	s_nop 0
	v_cndmask_b32_e32 v1, v1, v3, vcc
	v_rsq_f32_e32 v1, v1
	s_nop 0
	v_mul_f32_e32 v3, 0x45800000, v1
	v_cndmask_b32_e32 v46, v1, v3, vcc
	v_pk_mul_f32 v[20:21], v[20:21], v[46:47] op_sel_hi:[1,0]
	v_pk_mul_f32 v[24:25], v[24:25], v[46:47] op_sel_hi:[1,0]
	s_waitcnt vmcnt(0)
	v_pk_fma_f32 v[16:17], v[48:49], v[20:21], v[16:17]
	v_pk_mul_f32 v[20:21], v[22:23], v[46:47] op_sel_hi:[1,0]
	s_nop 0
	v_pk_fma_f32 v[18:19], v[50:51], v[20:21], v[18:19]
	v_mov_b64_e32 v[20:21], v[132:133]
	v_mov_b64_e32 v[22:23], v[134:135]
	v_pk_fma_f32 v[12:13], v[20:21], v[24:25], v[12:13]
	v_pk_mul_f32 v[20:21], v[26:27], v[46:47] op_sel_hi:[1,0]
	v_pk_mul_f32 v[24:25], v[28:29], v[46:47] op_sel_hi:[1,0]
	v_pk_fma_f32 v[14:15], v[22:23], v[20:21], v[14:15]
	v_mov_b64_e32 v[20:21], v[136:137]
	v_mov_b64_e32 v[22:23], v[138:139]
	v_pk_fma_f32 v[8:9], v[20:21], v[24:25], v[8:9]
	v_pk_mul_f32 v[20:21], v[30:31], v[46:47] op_sel_hi:[1,0]
	v_pk_mul_f32 v[24:25], v[32:33], v[46:47] op_sel_hi:[1,0]
	v_pk_fma_f32 v[10:11], v[22:23], v[20:21], v[10:11]
	v_mov_b64_e32 v[20:21], v[140:141]
	v_mov_b64_e32 v[22:23], v[142:143]
	v_pk_fma_f32 v[4:5], v[24:25], v[20:21], v[4:5]
	v_pk_mul_f32 v[20:21], v[34:35], v[46:47] op_sel_hi:[1,0]
	s_nop 0
	v_pk_fma_f32 v[6:7], v[20:21], v[22:23], v[6:7]

.LBB0_213:
	s_or_b64 exec, exec, s[22:23]
	s_waitcnt vmcnt(0)
	v_pk_mul_f32 v[50:51], v[20:21], v[20:21]
	v_pk_mul_f32 v[52:53], v[22:23], v[22:23]
	v_add_f32_e32 v50, v51, v50
	v_pk_mul_f32 v[54:55], v[24:25], v[24:25]
	v_add_f32_e32 v50, v52, v50
	v_add_f32_e32 v3, v55, v54
	v_add_f32_e32 v50, v53, v50
	global_load_dwordx4 v[52:55], v[38:39], off
	global_load_dwordx4 v[132:135], v[38:39], off offset:1024
	global_load_dwordx4 v[136:139], v[38:39], off offset:2048
	global_load_dwordx4 v[140:143], v[38:39], off offset:3072
	v_pk_mul_f32 v[56:57], v[26:27], v[26:27]
	v_pk_mul_f32 v[58:59], v[28:29], v[28:29]
	v_add_f32_e32 v3, v56, v3
	v_add_f32_e32 v3, v57, v3
	v_pk_mul_f32 v[60:61], v[30:31], v[30:31]
	v_add_f32_e32 v3, v50, v3
	v_add_f32_e32 v50, v59, v58
	v_add_f32_e32 v50, v60, v50
	v_pk_mul_f32 v[62:63], v[32:33], v[32:33]
	v_add_f32_e32 v50, v61, v50
	v_pk_mul_f32 v[64:65], v[34:35], v[34:35]
	v_add_f32_e32 v3, v3, v50
	v_add_f32_e32 v50, v63, v62
	v_add_f32_e32 v50, v64, v50
	v_add_f32_e32 v50, v65, v50
	v_add_f32_e32 v3, v3, v50
	v_and_b32_e32 v50, 64, v202
	v_add_u32_e32 v50, 64, v50
	v_xor_b32_e32 v51, 32, v202
	v_cmp_lt_i32_e32 vcc, v51, v50
	s_mov_b32 s6, 0x800000
	s_nop 0
	v_cndmask_b32_e32 v51, v202, v51, vcc
	v_lshlrev_b32_e32 v51, 2, v51
	ds_bpermute_b32 v51, v51, v3
	s_waitcnt lgkmcnt(0)
	v_add_f32_e32 v3, v3, v51
	v_xor_b32_e32 v51, 16, v202
	v_cmp_lt_i32_e32 vcc, v51, v50
	s_nop 1
	v_cndmask_b32_e32 v51, v202, v51, vcc
	v_lshlrev_b32_e32 v51, 2, v51
	ds_bpermute_b32 v51, v51, v3
	s_waitcnt lgkmcnt(0)
	v_add_f32_e32 v3, v3, v51
	v_xor_b32_e32 v51, 8, v202
	v_cmp_lt_i32_e32 vcc, v51, v50
	s_nop 1
	v_cndmask_b32_e32 v51, v202, v51, vcc
	v_lshlrev_b32_e32 v51, 2, v51
	ds_bpermute_b32 v51, v51, v3
	s_waitcnt lgkmcnt(0)
	v_add_f32_e32 v3, v3, v51
	v_xor_b32_e32 v51, 4, v202
	v_cmp_lt_i32_e32 vcc, v51, v50
	s_nop 1
	v_cndmask_b32_e32 v51, v202, v51, vcc
	v_lshlrev_b32_e32 v51, 2, v51
	ds_bpermute_b32 v51, v51, v3
	s_waitcnt lgkmcnt(0)
	v_add_f32_e32 v3, v3, v51
	v_xor_b32_e32 v51, 2, v202
	v_cmp_lt_i32_e32 vcc, v51, v50
	s_nop 1
	v_cndmask_b32_e32 v51, v202, v51, vcc
	v_lshlrev_b32_e32 v51, 2, v51
	ds_bpermute_b32 v51, v51, v3
	s_waitcnt lgkmcnt(0)
	v_add_f32_e32 v3, v3, v51
	v_xor_b32_e32 v51, 1, v202
	v_cmp_lt_i32_e32 vcc, v51, v50
	s_nop 1
	v_cndmask_b32_e32 v50, v202, v51, vcc
	v_lshlrev_b32_e32 v50, 2, v50
	ds_bpermute_b32 v50, v50, v3
	s_waitcnt lgkmcnt(0)
	v_add_f32_e32 v3, v3, v50
	v_fmamk_f32 v3, v3, 0x3a800000, v198
	v_cmp_gt_f32_e32 vcc, s6, v3
	v_mul_f32_e32 v50, 0x4b800000, v3
	s_nop 0
	v_cndmask_b32_e32 v3, v3, v50, vcc
	v_rsq_f32_e32 v3, v3
	s_nop 0
	v_mul_f32_e32 v50, 0x45800000, v3
	v_cndmask_b32_e32 v50, v3, v50, vcc
	v_pk_mul_f32 v[20:21], v[20:21], v[50:51] op_sel_hi:[1,0]
	v_pk_mul_f32 v[24:25], v[24:25], v[50:51] op_sel_hi:[1,0]
	s_waitcnt vmcnt(0)
	v_pk_fma_f32 v[16:17], v[52:53], v[20:21], v[16:17]
	v_pk_mul_f32 v[20:21], v[22:23], v[50:51] op_sel_hi:[1,0]
	s_nop 0
	v_pk_fma_f32 v[18:19], v[54:55], v[20:21], v[18:19]
	v_mov_b64_e32 v[20:21], v[132:133]
	v_mov_b64_e32 v[22:23], v[134:135]
	v_pk_fma_f32 v[12:13], v[20:21], v[24:25], v[12:13]
	v_pk_mul_f32 v[20:21], v[26:27], v[50:51] op_sel_hi:[1,0]
	v_pk_mul_f32 v[24:25], v[28:29], v[50:51] op_sel_hi:[1,0]
	v_pk_fma_f32 v[14:15], v[22:23], v[20:21], v[14:15]
	v_mov_b64_e32 v[20:21], v[136:137]
	v_mov_b64_e32 v[22:23], v[138:139]
	v_pk_fma_f32 v[8:9], v[20:21], v[24:25], v[8:9]
	v_pk_mul_f32 v[20:21], v[30:31], v[50:51] op_sel_hi:[1,0]
	v_pk_mul_f32 v[24:25], v[32:33], v[50:51] op_sel_hi:[1,0]
	v_pk_fma_f32 v[10:11], v[22:23], v[20:21], v[10:11]
	v_mov_b64_e32 v[20:21], v[140:141]
	v_mov_b64_e32 v[22:23], v[142:143]
	v_pk_fma_f32 v[4:5], v[24:25], v[20:21], v[4:5]
	v_pk_mul_f32 v[20:21], v[34:35], v[50:51] op_sel_hi:[1,0]
	s_nop 0
	v_pk_fma_f32 v[6:7], v[20:21], v[22:23], v[6:7]
.LBB0_214:
	v_readlane_b32 s6, v254, 28
	v_readlane_b32 s7, v254, 29
	s_andn2_b64 vcc, exec, s[6:7]
	s_waitcnt vmcnt(3)
	global_store_dwordx4 v[48:49], v[16:19], off
	s_waitcnt vmcnt(3)
	global_store_dwordx4 v[48:49], v[12:15], off offset:1024
	s_waitcnt vmcnt(3)
	global_store_dwordx4 v[48:49], v[8:11], off offset:2048
	s_waitcnt vmcnt(3)
	global_store_dwordx4 v[48:49], v[4:7], off offset:3072
	s_cbranch_vccnz .LBB0_195
	v_mov_b32_e32 v20, v12
	v_mov_b32_e32 v21, v16
	v_pk_mul_f32 v[20:21], v[20:21], v[20:21]
	v_mov_b32_e32 v22, v13
	v_mov_b32_e32 v23, v17
	v_pk_fma_f32 v[20:21], v[22:23], v[22:23], v[20:21]
	v_mov_b32_e32 v22, v14
	v_mov_b32_e32 v23, v18
	v_pk_fma_f32 v[20:21], v[22:23], v[22:23], v[20:21]
	v_mov_b32_e32 v22, v15
	v_mov_b32_e32 v23, v19
	v_pk_fma_f32 v[20:21], v[22:23], v[22:23], v[20:21]
	v_mov_b32_e32 v22, v4
	v_mov_b32_e32 v23, v8
	v_pk_mul_f32 v[22:23], v[22:23], v[22:23]
	v_mov_b32_e32 v24, v5
	v_mov_b32_e32 v25, v9
	v_pk_fma_f32 v[22:23], v[24:25], v[24:25], v[22:23]
	v_mov_b32_e32 v24, v6
	v_mov_b32_e32 v25, v10
	v_pk_fma_f32 v[22:23], v[24:25], v[24:25], v[22:23]
	v_mov_b32_e32 v24, v7
	v_mov_b32_e32 v25, v11
	v_pk_fma_f32 v[22:23], v[24:25], v[24:25], v[22:23]
	global_load_dwordx4 v[24:27], v[42:43], off
	global_load_dwordx4 v[144:147], v[42:43], off offset:1024
	global_load_dwordx4 v[148:151], v[42:43], off offset:2048
	global_load_dwordx4 v[152:155], v[42:43], off offset:3072
	v_add_f32_e32 v3, v20, v21
	v_and_b32_e32 v20, 64, v202
	v_add_u32_e32 v20, 64, v20
	v_xor_b32_e32 v21, 32, v202
	v_cmp_lt_i32_e32 vcc, v21, v20
	v_add_f32_e32 v3, v23, v3
	v_add_f32_e32 v3, v22, v3
	v_cndmask_b32_e32 v21, v202, v21, vcc
	v_lshlrev_b32_e32 v21, 2, v21
	ds_bpermute_b32 v21, v21, v3
	s_mov_b32 s6, 0x800000
	s_waitcnt lgkmcnt(0)
	v_add_f32_e32 v3, v3, v21
	v_xor_b32_e32 v21, 16, v202
	v_cmp_lt_i32_e32 vcc, v21, v20
	s_nop 1
	v_cndmask_b32_e32 v21, v202, v21, vcc
	v_lshlrev_b32_e32 v21, 2, v21
	ds_bpermute_b32 v21, v21, v3
	s_waitcnt lgkmcnt(0)
	v_add_f32_e32 v3, v3, v21
	v_xor_b32_e32 v21, 8, v202
	v_cmp_lt_i32_e32 vcc, v21, v20
	s_nop 1
	v_cndmask_b32_e32 v21, v202, v21, vcc
	v_lshlrev_b32_e32 v21, 2, v21
	ds_bpermute_b32 v21, v21, v3
	s_waitcnt lgkmcnt(0)
	v_add_f32_e32 v3, v3, v21
	v_xor_b32_e32 v21, 4, v202
	v_cmp_lt_i32_e32 vcc, v21, v20
	s_nop 1
	v_cndmask_b32_e32 v21, v202, v21, vcc
	v_lshlrev_b32_e32 v21, 2, v21
	ds_bpermute_b32 v21, v21, v3
	s_waitcnt lgkmcnt(0)
	v_add_f32_e32 v3, v3, v21
	v_xor_b32_e32 v21, 2, v202
	v_cmp_lt_i32_e32 vcc, v21, v20
	s_nop 1
	v_cndmask_b32_e32 v21, v202, v21, vcc
	v_lshlrev_b32_e32 v21, 2, v21
	ds_bpermute_b32 v21, v21, v3
	s_waitcnt lgkmcnt(0)
	v_add_f32_e32 v3, v3, v21
	v_xor_b32_e32 v21, 1, v202
	v_cmp_lt_i32_e32 vcc, v21, v20
	s_nop 1
	v_cndmask_b32_e32 v20, v202, v21, vcc
	v_lshlrev_b32_e32 v20, 2, v20
	ds_bpermute_b32 v20, v20, v3
	s_waitcnt lgkmcnt(0)
	v_add_f32_e32 v3, v3, v20
	v_fmamk_f32 v3, v3, 0x3a800000, v198
	v_cmp_gt_f32_e32 vcc, s6, v3
	v_mul_f32_e32 v20, 0x4b800000, v3
	s_nop 0
	v_cndmask_b32_e32 v3, v3, v20, vcc
	v_rsq_f32_e32 v3, v3
	s_nop 0
	v_mul_f32_e32 v20, 0x45800000, v3
	v_cndmask_b32_e32 v22, v3, v20, vcc
	v_pk_mul_f32 v[16:17], v[16:17], v[22:23] op_sel_hi:[1,0]
	v_pk_mul_f32 v[18:19], v[18:19], v[22:23] op_sel_hi:[1,0]
	v_lshlrev_b64 v[20:21], 11, v[0:1]
	s_waitcnt vmcnt(0)
	v_pk_mul_f32 v[16:17], v[24:25], v[16:17]
	v_pk_mul_f32 v[18:19], v[26:27], v[18:19]
	v_lshl_add_u64 v[20:21], v[44:45], 0, v[20:21]
	v_cvt_pk_bf16_f32 v16, v16, v17
	v_cvt_pk_bf16_f32 v17, v18, v19
	global_store_dwordx2 v[20:21], v[16:17], off
	v_mov_b64_e32 v[16:17], v[144:145]
	v_mov_b64_e32 v[18:19], v[146:147]
	v_pk_mul_f32 v[12:13], v[12:13], v[22:23] op_sel_hi:[1,0]
	v_pk_mul_f32 v[14:15], v[14:15], v[22:23] op_sel_hi:[1,0]
	v_pk_mul_f32 v[8:9], v[8:9], v[22:23] op_sel_hi:[1,0]
	v_pk_mul_f32 v[10:11], v[10:11], v[22:23] op_sel_hi:[1,0]
	v_pk_mul_f32 v[4:5], v[4:5], v[22:23] op_sel_hi:[1,0]
	v_pk_mul_f32 v[6:7], v[6:7], v[22:23] op_sel_hi:[1,0]
	v_pk_mul_f32 v[12:13], v[16:17], v[12:13]
	v_pk_mul_f32 v[14:15], v[18:19], v[14:15]
	v_cvt_pk_bf16_f32 v12, v12, v13
	v_cvt_pk_bf16_f32 v13, v14, v15
	global_store_dwordx2 v[20:21], v[12:13], off offset:512
	v_mov_b64_e32 v[12:13], v[148:149]
	v_mov_b64_e32 v[14:15], v[150:151]
	v_pk_mul_f32 v[8:9], v[8:9], v[12:13]
	v_pk_mul_f32 v[10:11], v[10:11], v[14:15]
	v_cvt_pk_bf16_f32 v8, v8, v9
	v_cvt_pk_bf16_f32 v9, v10, v11
	global_store_dwordx2 v[20:21], v[8:9], off offset:1024
	v_mov_b64_e32 v[8:9], v[152:153]
	v_mov_b64_e32 v[10:11], v[154:155]
	v_pk_mul_f32 v[4:5], v[4:5], v[8:9]
	v_pk_mul_f32 v[6:7], v[6:7], v[10:11]
	v_cvt_pk_bf16_f32 v4, v4, v5
	v_cvt_pk_bf16_f32 v5, v6, v7
	global_store_dwordx2 v[20:21], v[4:5], off offset:1536
	s_branch .LBB0_195

.LBB0_988:
	s_or_b64 exec, exec, s[22:23]
	s_waitcnt vmcnt(0)
	v_pk_mul_f32 v[50:51], v[20:21], v[20:21]
	v_pk_mul_f32 v[52:53], v[22:23], v[22:23]
	v_add_f32_e32 v50, v51, v50
	v_pk_mul_f32 v[54:55], v[24:25], v[24:25]
	v_add_f32_e32 v50, v52, v50
	v_add_f32_e32 v3, v55, v54
	v_add_f32_e32 v50, v53, v50
	global_load_dwordx4 v[52:55], v[38:39], off
	global_load_dwordx4 v[132:135], v[38:39], off offset:1024
	global_load_dwordx4 v[136:139], v[38:39], off offset:2048
	global_load_dwordx4 v[140:143], v[38:39], off offset:3072
	v_pk_mul_f32 v[56:57], v[26:27], v[26:27]
	v_pk_mul_f32 v[58:59], v[28:29], v[28:29]
	v_add_f32_e32 v3, v56, v3
	v_add_f32_e32 v3, v57, v3
	v_pk_mul_f32 v[60:61], v[30:31], v[30:31]
	v_add_f32_e32 v3, v50, v3
	v_add_f32_e32 v50, v59, v58
	v_add_f32_e32 v50, v60, v50
	v_pk_mul_f32 v[62:63], v[32:33], v[32:33]
	v_add_f32_e32 v50, v61, v50
	v_pk_mul_f32 v[64:65], v[34:35], v[34:35]
	v_add_f32_e32 v3, v3, v50
	v_add_f32_e32 v50, v63, v62
	v_add_f32_e32 v50, v64, v50
	v_add_f32_e32 v50, v65, v50
	v_add_f32_e32 v3, v3, v50
	v_and_b32_e32 v50, 64, v202
	v_add_u32_e32 v50, 64, v50
	v_xor_b32_e32 v51, 32, v202
	v_cmp_lt_i32_e32 vcc, v51, v50
	s_mov_b32 s4, 0x800000
	s_nop 0
	v_cndmask_b32_e32 v51, v202, v51, vcc
	v_lshlrev_b32_e32 v51, 2, v51
	ds_bpermute_b32 v51, v51, v3
	s_waitcnt lgkmcnt(0)
	v_add_f32_e32 v3, v3, v51
	v_xor_b32_e32 v51, 16, v202
	v_cmp_lt_i32_e32 vcc, v51, v50
	s_nop 1
	v_cndmask_b32_e32 v51, v202, v51, vcc
	v_lshlrev_b32_e32 v51, 2, v51
	ds_bpermute_b32 v51, v51, v3
	s_waitcnt lgkmcnt(0)
	v_add_f32_e32 v3, v3, v51
	v_xor_b32_e32 v51, 8, v202
	v_cmp_lt_i32_e32 vcc, v51, v50
	s_nop 1
	v_cndmask_b32_e32 v51, v202, v51, vcc
	v_lshlrev_b32_e32 v51, 2, v51
	ds_bpermute_b32 v51, v51, v3
	s_waitcnt lgkmcnt(0)
	v_add_f32_e32 v3, v3, v51
	v_xor_b32_e32 v51, 4, v202
	v_cmp_lt_i32_e32 vcc, v51, v50
	s_nop 1
	v_cndmask_b32_e32 v51, v202, v51, vcc
	v_lshlrev_b32_e32 v51, 2, v51
	ds_bpermute_b32 v51, v51, v3
	s_waitcnt lgkmcnt(0)
	v_add_f32_e32 v3, v3, v51
	v_xor_b32_e32 v51, 2, v202
	v_cmp_lt_i32_e32 vcc, v51, v50
	s_nop 1
	v_cndmask_b32_e32 v51, v202, v51, vcc
	v_lshlrev_b32_e32 v51, 2, v51
	ds_bpermute_b32 v51, v51, v3
	s_waitcnt lgkmcnt(0)
	v_add_f32_e32 v3, v3, v51
	v_xor_b32_e32 v51, 1, v202
	v_cmp_lt_i32_e32 vcc, v51, v50
	s_nop 1
	v_cndmask_b32_e32 v50, v202, v51, vcc
	v_lshlrev_b32_e32 v50, 2, v50
	ds_bpermute_b32 v50, v50, v3
	s_waitcnt lgkmcnt(0)
	v_add_f32_e32 v3, v3, v50
	v_fmamk_f32 v3, v3, 0x3a800000, v198
	v_cmp_gt_f32_e32 vcc, s4, v3
	v_mul_f32_e32 v50, 0x4b800000, v3
	s_nop 0
	v_cndmask_b32_e32 v3, v3, v50, vcc
	v_rsq_f32_e32 v3, v3
	s_nop 0
	v_mul_f32_e32 v50, 0x45800000, v3
	v_cndmask_b32_e32 v50, v3, v50, vcc
	v_pk_mul_f32 v[20:21], v[20:21], v[50:51] op_sel_hi:[1,0]
	v_pk_mul_f32 v[24:25], v[24:25], v[50:51] op_sel_hi:[1,0]
	s_waitcnt vmcnt(0)
	v_pk_fma_f32 v[16:17], v[52:53], v[20:21], v[16:17]
	v_pk_mul_f32 v[20:21], v[22:23], v[50:51] op_sel_hi:[1,0]
	s_nop 0
	v_pk_fma_f32 v[18:19], v[54:55], v[20:21], v[18:19]
	v_mov_b64_e32 v[20:21], v[132:133]
	v_mov_b64_e32 v[22:23], v[134:135]
	v_pk_fma_f32 v[12:13], v[20:21], v[24:25], v[12:13]
	v_pk_mul_f32 v[20:21], v[26:27], v[50:51] op_sel_hi:[1,0]
	v_pk_mul_f32 v[24:25], v[28:29], v[50:51] op_sel_hi:[1,0]
	v_pk_fma_f32 v[14:15], v[22:23], v[20:21], v[14:15]
	v_mov_b64_e32 v[20:21], v[136:137]
	v_mov_b64_e32 v[22:23], v[138:139]
	v_pk_fma_f32 v[8:9], v[20:21], v[24:25], v[8:9]
	v_pk_mul_f32 v[20:21], v[30:31], v[50:51] op_sel_hi:[1,0]
	v_pk_mul_f32 v[24:25], v[32:33], v[50:51] op_sel_hi:[1,0]
	v_pk_fma_f32 v[10:11], v[22:23], v[20:21], v[10:11]
	v_mov_b64_e32 v[20:21], v[140:141]
	v_mov_b64_e32 v[22:23], v[142:143]
	v_pk_fma_f32 v[4:5], v[24:25], v[20:21], v[4:5]
	v_pk_mul_f32 v[20:21], v[34:35], v[50:51] op_sel_hi:[1,0]
	s_nop 0
	v_pk_fma_f32 v[6:7], v[20:21], v[22:23], v[6:7]
.LBB0_989:
	v_readlane_b32 s4, v254, 28
	v_readlane_b32 s5, v254, 29
	s_andn2_b64 vcc, exec, s[4:5]
	s_waitcnt vmcnt(3)
	global_store_dwordx4 v[48:49], v[16:19], off
	s_waitcnt vmcnt(3)
	global_store_dwordx4 v[48:49], v[12:15], off offset:1024
	s_waitcnt vmcnt(3)
	global_store_dwordx4 v[48:49], v[8:11], off offset:2048
	s_waitcnt vmcnt(3)
	global_store_dwordx4 v[48:49], v[4:7], off offset:3072
	s_cbranch_vccnz .LBB0_970
	v_mov_b32_e32 v20, v12
	v_mov_b32_e32 v21, v16
	v_pk_mul_f32 v[20:21], v[20:21], v[20:21]
	v_mov_b32_e32 v22, v13
	v_mov_b32_e32 v23, v17
	v_pk_fma_f32 v[20:21], v[22:23], v[22:23], v[20:21]
	v_mov_b32_e32 v22, v14
	v_mov_b32_e32 v23, v18
	v_pk_fma_f32 v[20:21], v[22:23], v[22:23], v[20:21]
	v_mov_b32_e32 v22, v15
	v_mov_b32_e32 v23, v19
	v_pk_fma_f32 v[20:21], v[22:23], v[22:23], v[20:21]
	v_mov_b32_e32 v22, v4
	v_mov_b32_e32 v23, v8
	v_pk_mul_f32 v[22:23], v[22:23], v[22:23]
	v_mov_b32_e32 v24, v5
	v_mov_b32_e32 v25, v9
	v_pk_fma_f32 v[22:23], v[24:25], v[24:25], v[22:23]
	v_mov_b32_e32 v24, v6
	v_mov_b32_e32 v25, v10
	v_pk_fma_f32 v[22:23], v[24:25], v[24:25], v[22:23]
	v_mov_b32_e32 v24, v7
	v_mov_b32_e32 v25, v11
	v_pk_fma_f32 v[22:23], v[24:25], v[24:25], v[22:23]
	global_load_dwordx4 v[24:27], v[42:43], off
	global_load_dwordx4 v[144:147], v[42:43], off offset:1024
	global_load_dwordx4 v[148:151], v[42:43], off offset:2048
	global_load_dwordx4 v[152:155], v[42:43], off offset:3072
	v_add_f32_e32 v3, v20, v21
	v_and_b32_e32 v20, 64, v202
	v_add_u32_e32 v20, 64, v20
	v_xor_b32_e32 v21, 32, v202
	v_cmp_lt_i32_e32 vcc, v21, v20
	v_add_f32_e32 v3, v23, v3
	v_add_f32_e32 v3, v22, v3
	v_cndmask_b32_e32 v21, v202, v21, vcc
	v_lshlrev_b32_e32 v21, 2, v21
	ds_bpermute_b32 v21, v21, v3
	s_mov_b32 s4, 0x800000
	s_waitcnt lgkmcnt(0)
	v_add_f32_e32 v3, v3, v21
	v_xor_b32_e32 v21, 16, v202
	v_cmp_lt_i32_e32 vcc, v21, v20
	s_nop 1
	v_cndmask_b32_e32 v21, v202, v21, vcc
	v_lshlrev_b32_e32 v21, 2, v21
	ds_bpermute_b32 v21, v21, v3
	s_waitcnt lgkmcnt(0)
	v_add_f32_e32 v3, v3, v21
	v_xor_b32_e32 v21, 8, v202
	v_cmp_lt_i32_e32 vcc, v21, v20
	s_nop 1
	v_cndmask_b32_e32 v21, v202, v21, vcc
	v_lshlrev_b32_e32 v21, 2, v21
	ds_bpermute_b32 v21, v21, v3
	s_waitcnt lgkmcnt(0)
	v_add_f32_e32 v3, v3, v21
	v_xor_b32_e32 v21, 4, v202
	v_cmp_lt_i32_e32 vcc, v21, v20
	s_nop 1
	v_cndmask_b32_e32 v21, v202, v21, vcc
	v_lshlrev_b32_e32 v21, 2, v21
	ds_bpermute_b32 v21, v21, v3
	s_waitcnt lgkmcnt(0)
	v_add_f32_e32 v3, v3, v21
	v_xor_b32_e32 v21, 2, v202
	v_cmp_lt_i32_e32 vcc, v21, v20
	s_nop 1
	v_cndmask_b32_e32 v21, v202, v21, vcc
	v_lshlrev_b32_e32 v21, 2, v21
	ds_bpermute_b32 v21, v21, v3
	s_waitcnt lgkmcnt(0)
	v_add_f32_e32 v3, v3, v21
	v_xor_b32_e32 v21, 1, v202
	v_cmp_lt_i32_e32 vcc, v21, v20
	s_nop 1
	v_cndmask_b32_e32 v20, v202, v21, vcc
	v_lshlrev_b32_e32 v20, 2, v20
	ds_bpermute_b32 v20, v20, v3
	s_waitcnt lgkmcnt(0)
	v_add_f32_e32 v3, v3, v20
	v_fmamk_f32 v3, v3, 0x3a800000, v198
	v_cmp_gt_f32_e32 vcc, s4, v3
	v_mul_f32_e32 v20, 0x4b800000, v3
	s_nop 0
	v_cndmask_b32_e32 v3, v3, v20, vcc
	v_rsq_f32_e32 v3, v3
	s_nop 0
	v_mul_f32_e32 v20, 0x45800000, v3
	v_cndmask_b32_e32 v22, v3, v20, vcc
	v_pk_mul_f32 v[16:17], v[16:17], v[22:23] op_sel_hi:[1,0]
	v_pk_mul_f32 v[18:19], v[18:19], v[22:23] op_sel_hi:[1,0]
	v_lshlrev_b64 v[20:21], 11, v[0:1]
	s_waitcnt vmcnt(0)
	v_pk_mul_f32 v[16:17], v[24:25], v[16:17]
	v_pk_mul_f32 v[18:19], v[26:27], v[18:19]
	v_lshl_add_u64 v[20:21], v[44:45], 0, v[20:21]
	v_cvt_pk_bf16_f32 v16, v16, v17
	v_cvt_pk_bf16_f32 v17, v18, v19
	global_store_dwordx2 v[20:21], v[16:17], off
	v_mov_b64_e32 v[16:17], v[144:145]
	v_mov_b64_e32 v[18:19], v[146:147]
	v_pk_mul_f32 v[12:13], v[12:13], v[22:23] op_sel_hi:[1,0]
	v_pk_mul_f32 v[14:15], v[14:15], v[22:23] op_sel_hi:[1,0]
	v_pk_mul_f32 v[8:9], v[8:9], v[22:23] op_sel_hi:[1,0]
	v_pk_mul_f32 v[10:11], v[10:11], v[22:23] op_sel_hi:[1,0]
	v_pk_mul_f32 v[4:5], v[4:5], v[22:23] op_sel_hi:[1,0]
	v_pk_mul_f32 v[6:7], v[6:7], v[22:23] op_sel_hi:[1,0]
	v_pk_mul_f32 v[12:13], v[16:17], v[12:13]
	v_pk_mul_f32 v[14:15], v[18:19], v[14:15]
	v_cvt_pk_bf16_f32 v12, v12, v13
	v_cvt_pk_bf16_f32 v13, v14, v15
	global_store_dwordx2 v[20:21], v[12:13], off offset:512
	v_mov_b64_e32 v[12:13], v[148:149]
	v_mov_b64_e32 v[14:15], v[150:151]
	v_pk_mul_f32 v[8:9], v[8:9], v[12:13]
	v_pk_mul_f32 v[10:11], v[10:11], v[14:15]
	v_cvt_pk_bf16_f32 v8, v8, v9
	v_cvt_pk_bf16_f32 v9, v10, v11
	global_store_dwordx2 v[20:21], v[8:9], off offset:1024
	v_mov_b64_e32 v[8:9], v[152:153]
	v_mov_b64_e32 v[10:11], v[154:155]
	v_pk_mul_f32 v[4:5], v[4:5], v[8:9]
	v_pk_mul_f32 v[6:7], v[6:7], v[10:11]
	v_cvt_pk_bf16_f32 v4, v4, v5
	v_cvt_pk_bf16_f32 v5, v6, v7
	global_store_dwordx2 v[20:21], v[4:5], off offset:1536
	s_branch .LBB0_970
